# attention main loop back edge rotated (loop bookkeeping moved in front of the barrier) plus MLP-in row-scale loads hoisted to tile start
# baseline (speedup 1.0000x reference)
; #define DMA_K(t, slot) do { const bf16* g_ = kg + (size_t)(t) * tstep; DMA16(g_, kgo, lds + (slot) + wl); DMA16(g_ + (size_t)64 * PW, kgo, lds + (slot) + 8192 + wl); } while (0)
; __device__ __forceinline__ void flash_map(f32x16 (&O)[4], LAS unsigned char* lds, const bf16* QKV, int qcol, int kcol, int vcol, int qb, int w, int lane, int tid) {
;     ...
;     for (int kt = 0; kt < nkt; ++kt) {
;         const int buf = kt & 1;
;         const bool more = kt + 1 < nkt;
;         if (kt + 2 < nkt) DMA_K(kt + 2, kb2);
;     ...
;         asm volatile("s_waitcnt vmcnt(0) lgkmcnt(0)\n\ts_barrier" ::: "memory");
;         const int t0 = kb0; kb0 = kb1; kb1 = kb2; kb2 = t0;
.Lda_h4_done:
	s_add_u32 s10, s10, 0x180000
	s_addc_u32 s11, s11, 0
	s_add_i32 s6, s6, 0x8000
	s_add_u32 s12, s12, 0x180000
	s_addc_u32 s13, s13, 0
	v_add_u32_e32 v237, 0x80, v237
	s_mov_b32 s4, s16
	s_mov_b32 s16, s9
	s_mov_b32 s9, s17
	s_mov_b32 s22, s18
	s_mov_b32 s17, s4
	s_and_b32 s20, s6, 0x8000
	s_add_i32 s18, s22, 1
	s_mov_b32 s21, s17
	s_mov_b32 s19, s20
	v_add3_u32 v156, s19, v213, v229
	v_add3_u32 v157, s19, v213, v230
	v_add3_u32 v158, s19, v213, v231
	v_add3_u32 v159, s19, v213, v232
	s_add_i32 s14, s9, s23
	s_waitcnt vmcnt(0) lgkmcnt(0)
	s_barrier
	s_cmp_ge_i32 s22, s74
	s_cbranch_scc1 .LBB0_201
	s_mov_b32 s15, m0
	s_mov_b32 m0, s14
	s_add_u32 s4, s10, 0xc0000
	s_addc_u32 s5, s11, 0
	global_load_lds_dwordx4 v210, s[10:11]
	s_add_i32 m0, s14, 0x2000
	s_nop 0
	global_load_lds_dwordx4 v210, s[4:5]
	s_mov_b32 m0, s15
	s_branch .Lda_h1_body
